# grid barrier: acquire invalidate issued right after the arrive atomic (overlaps the poll round trip)
# speedup vs baseline: 1.0131x; 1.0081x over previous
; __device__ __forceinline__ unsigned xb_ld(unsigned* p)              { return __hip_atomic_load(p, __ATOMIC_RELAXED, __HIP_MEMORY_SCOPE_AGENT); }
; __device__ __forceinline__ unsigned xb_add(unsigned* p, unsigned v) { return __hip_atomic_fetch_add(p, v, __ATOMIC_RELAXED, __HIP_MEMORY_SCOPE_AGENT); }
; #define XB_SPIN(cond, bar) do { unsigned _sp = 0; while (cond) { __builtin_amdgcn_s_sleep(1); \
;     if ((++_sp & 255u) == 0u) { if (xb_ld(&(bar)[XB_TMO])) break; if (_sp > XB_SPIN_CAP) { atomicAdd(&(bar)[XB_TMO], 1u); break; } } } } while (0)
; __device__ __forceinline__ void xcd_barrier(const XcdBarrier& b) {
;     ...
;         unsigned nloc = b.st[0], nx = b.st[1];
;         if (nloc == 0u) { xcd_barrier_complete(bar, b.x, nloc, nx); b.st[0] = nloc; b.st[1] = nx; }
;         const unsigned old = xb_add(&bar[XB_XSUB(b.x)], 1u);
;         const unsigned gen = old / nloc;
;         if (old + 1u == (gen + 1u) * nloc) {
;             __builtin_amdgcn_fence(__ATOMIC_RELEASE, "agent");
;             asm volatile("s_waitcnt vmcnt(0)" ::: "memory");
;             const unsigned og = xb_add(&bar[XB_TOP], 1u);
;             const unsigned tg = og / nx;
;             if (og + 1u == (tg + 1u) * nx) xb_add(&bar[XB_TOPGEN], 1u);
;             else XB_SPIN(xb_ld(&bar[XB_TOPGEN]) == tg, bar);
;             __builtin_amdgcn_fence(__ATOMIC_ACQUIRE, "agent");
;             asm volatile("s_waitcnt vmcnt(0)" ::: "memory");
;         } else {
;             XB_SPIN(xb_ld(&bar[XB_TOPGEN]) == gen, bar);
.LBB0_93:
	s_lshl_b32 s3, s2, 8
	v_readlane_b32 s4, v252, 8
	v_readlane_b32 s5, v252, 9
	s_add_u32 s4, s4, s3
	s_addc_u32 s5, s5, 0
	v_mov_b32_e32 v2, 0x1000
	v_mov_b32_e32 v4, 1
	v_sub_u32_e32 v5, 0, v3
	global_atomic_add v4, v2, v4, s[4:5] offset:1024 sc0
	buffer_inv sc1
	v_cvt_f32_u32_e32 v2, v3
	v_rcp_iflag_f32_e32 v2, v2
	s_nop 0
	v_mul_f32_e32 v2, 0x4f7ffffe, v2
	v_cvt_u32_f32_e32 v2, v2
	v_mul_lo_u32 v5, v5, v2
	v_mul_hi_u32 v5, v2, v5
	v_add_u32_e32 v2, v2, v5
	s_waitcnt vmcnt(0)
	v_mul_hi_u32 v2, v4, v2
	v_mul_lo_u32 v5, v2, v3
	v_sub_u32_e32 v5, v4, v5
	v_add_u32_e32 v6, 1, v2
	v_cmp_ge_u32_e32 vcc, v5, v3
	v_add_u32_e32 v4, 1, v4
	s_nop 0
	v_cndmask_b32_e32 v2, v2, v6, vcc
	v_sub_u32_e32 v6, v5, v3
	v_cndmask_b32_e32 v5, v5, v6, vcc
	v_add_u32_e32 v6, 1, v2
	v_cmp_ge_u32_e32 vcc, v5, v3
	s_nop 1
	v_cndmask_b32_e32 v2, v2, v6, vcc
	v_mul_lo_u32 v5, v3, v2
	v_add_u32_e32 v3, v5, v3
	v_cmp_ne_u32_e32 vcc, v4, v3
	s_and_saveexec_b64 s[4:5], vcc
	s_xor_b64 s[4:5], exec, s[4:5]
	s_cbranch_execz .LBB0_107
	v_readlane_b32 s6, v252, 8
	s_waitcnt lgkmcnt(0)
	v_mov_b32_e32 v1, 0x3000
	v_readlane_b32 s7, v252, 9
	s_add_u32 s8, s6, 0x3500
	s_addc_u32 s9, s7, 0
	s_nop 2
	global_load_dword v1, v1, s[6:7] offset:1280 sc1
	s_waitcnt vmcnt(0)
	v_cmp_eq_u32_e32 vcc, v1, v2
	s_and_saveexec_b64 s[6:7], vcc
	s_cbranch_execz .LBB0_106
	s_mov_b32 s3, 1
	s_mov_b64 s[10:11], 0
	v_mov_b32_e32 v1, 0
	s_branch .LBB0_97

; __device__ __forceinline__ unsigned xb_ld(unsigned* p)              { return __hip_atomic_load(p, __ATOMIC_RELAXED, __HIP_MEMORY_SCOPE_AGENT); }
; #define XB_SPIN(cond, bar) do { unsigned _sp = 0; while (cond) { __builtin_amdgcn_s_sleep(1); \
;     if ((++_sp & 255u) == 0u) { if (xb_ld(&(bar)[XB_TMO])) break; if (_sp > XB_SPIN_CAP) { atomicAdd(&(bar)[XB_TMO], 1u); break; } } } } while (0)
; __device__ __forceinline__ void xcd_barrier(const XcdBarrier& b) {
;     ...
;             XB_SPIN(xb_ld(&bar[XB_TOPGEN]) == gen, bar);
;             __builtin_amdgcn_fence(__ATOMIC_ACQUIRE, "agent");
;             asm volatile("s_waitcnt vmcnt(0)" ::: "memory");
.LBB0_106:
	s_or_b64 exec, exec, s[6:7]
	s_waitcnt vmcnt(0)
	s_waitcnt vmcnt(0)

; __device__ __forceinline__ void xcd_barrier(const XcdBarrier& b) {
;     ...
;             __builtin_amdgcn_fence(__ATOMIC_ACQUIRE, "agent");
;             asm volatile("s_waitcnt vmcnt(0)" ::: "memory");
.LBB0_124:
	s_or_b64 exec, exec, s[4:5]
	s_waitcnt vmcnt(0)
	s_waitcnt vmcnt(0)

; __device__ __forceinline__ unsigned xb_ld(unsigned* p)              { return __hip_atomic_load(p, __ATOMIC_RELAXED, __HIP_MEMORY_SCOPE_AGENT); }
; __device__ __forceinline__ unsigned xb_add(unsigned* p, unsigned v) { return __hip_atomic_fetch_add(p, v, __ATOMIC_RELAXED, __HIP_MEMORY_SCOPE_AGENT); }
; #define XB_SPIN(cond, bar) do { unsigned _sp = 0; while (cond) { __builtin_amdgcn_s_sleep(1); \
;     if ((++_sp & 255u) == 0u) { if (xb_ld(&(bar)[XB_TMO])) break; if (_sp > XB_SPIN_CAP) { atomicAdd(&(bar)[XB_TMO], 1u); break; } } } } while (0)
; __device__ __forceinline__ void xcd_barrier(const XcdBarrier& b) {
;     ...
;         unsigned nloc = b.st[0], nx = b.st[1];
;         if (nloc == 0u) { xcd_barrier_complete(bar, b.x, nloc, nx); b.st[0] = nloc; b.st[1] = nx; }
;         const unsigned old = xb_add(&bar[XB_XSUB(b.x)], 1u);
;         const unsigned gen = old / nloc;
;         if (old + 1u == (gen + 1u) * nloc) {
;             __builtin_amdgcn_fence(__ATOMIC_RELEASE, "agent");
;             asm volatile("s_waitcnt vmcnt(0)" ::: "memory");
;             const unsigned og = xb_add(&bar[XB_TOP], 1u);
;             const unsigned tg = og / nx;
;             if (og + 1u == (tg + 1u) * nx) xb_add(&bar[XB_TOPGEN], 1u);
;             else XB_SPIN(xb_ld(&bar[XB_TOPGEN]) == tg, bar);
;             __builtin_amdgcn_fence(__ATOMIC_ACQUIRE, "agent");
;             asm volatile("s_waitcnt vmcnt(0)" ::: "memory");
;         } else {
;             XB_SPIN(xb_ld(&bar[XB_TOPGEN]) == gen, bar);
.LBB0_333:
	v_readlane_b32 s4, v253, 35
	v_readlane_b32 s5, v253, 36
	v_cvt_f32_u32_e32 v1, v2
	v_sub_u32_e32 v4, 0, v2
	v_rcp_iflag_f32_e32 v1, v1
	s_nop 1
	global_atomic_add v3, v177, v238, s[4:5] sc0
	buffer_inv sc1
	v_mul_f32_e32 v1, 0x4f7ffffe, v1
	v_cvt_u32_f32_e32 v1, v1
	v_mul_lo_u32 v4, v4, v1
	v_mul_hi_u32 v4, v1, v4
	v_add_u32_e32 v1, v1, v4
	s_waitcnt vmcnt(0)
	v_mul_hi_u32 v1, v3, v1
	v_mul_lo_u32 v4, v1, v2
	v_sub_u32_e32 v4, v3, v4
	v_add_u32_e32 v5, 1, v1
	v_cmp_ge_u32_e32 vcc, v4, v2
	v_add_u32_e32 v3, 1, v3
	s_nop 0
	v_cndmask_b32_e32 v1, v1, v5, vcc
	v_sub_u32_e32 v5, v4, v2
	v_cndmask_b32_e32 v4, v4, v5, vcc
	v_add_u32_e32 v5, 1, v1
	v_cmp_ge_u32_e32 vcc, v4, v2
	s_nop 1
	v_cndmask_b32_e32 v1, v1, v5, vcc
	v_mul_lo_u32 v4, v2, v1
	v_add_u32_e32 v2, v4, v2
	v_cmp_ne_u32_e32 vcc, v3, v2
	s_and_saveexec_b64 s[4:5], vcc
	s_xor_b64 s[4:5], exec, s[4:5]
	s_cbranch_execz .LBB0_347
	v_readlane_b32 s8, v253, 37
	v_readlane_b32 s9, v253, 38
	s_waitcnt lgkmcnt(0)
	s_nop 3
	global_load_dword v0, v177, s[8:9] sc1
	s_waitcnt vmcnt(0)
	v_cmp_eq_u32_e32 vcc, v0, v1
	s_and_saveexec_b64 s[8:9], vcc
	s_cbranch_execz .LBB0_346
	s_mov_b32 s3, 1
	s_mov_b64 s[16:17], 0
	s_branch .LBB0_337

; __device__ __forceinline__ unsigned xb_ld(unsigned* p)              { return __hip_atomic_load(p, __ATOMIC_RELAXED, __HIP_MEMORY_SCOPE_AGENT); }
; #define XB_SPIN(cond, bar) do { unsigned _sp = 0; while (cond) { __builtin_amdgcn_s_sleep(1); \
;     if ((++_sp & 255u) == 0u) { if (xb_ld(&(bar)[XB_TMO])) break; if (_sp > XB_SPIN_CAP) { atomicAdd(&(bar)[XB_TMO], 1u); break; } } } } while (0)
; __device__ __forceinline__ void xcd_barrier(const XcdBarrier& b) {
;     ...
;             XB_SPIN(xb_ld(&bar[XB_TOPGEN]) == gen, bar);
;             __builtin_amdgcn_fence(__ATOMIC_ACQUIRE, "agent");
;             asm volatile("s_waitcnt vmcnt(0)" ::: "memory");
.LBB0_346:
	s_or_b64 exec, exec, s[8:9]
	s_waitcnt vmcnt(0)
	s_waitcnt vmcnt(0)

; __device__ __forceinline__ unsigned xb_ld(unsigned* p)              { return __hip_atomic_load(p, __ATOMIC_RELAXED, __HIP_MEMORY_SCOPE_AGENT); }
; __device__ __forceinline__ unsigned xb_add(unsigned* p, unsigned v) { return __hip_atomic_fetch_add(p, v, __ATOMIC_RELAXED, __HIP_MEMORY_SCOPE_AGENT); }
; #define XB_SPIN(cond, bar) do { unsigned _sp = 0; while (cond) { __builtin_amdgcn_s_sleep(1); \
;     if ((++_sp & 255u) == 0u) { if (xb_ld(&(bar)[XB_TMO])) break; if (_sp > XB_SPIN_CAP) { atomicAdd(&(bar)[XB_TMO], 1u); break; } } } } while (0)
; __device__ __forceinline__ void xcd_barrier(const XcdBarrier& b) {
;     ...
;         unsigned nloc = b.st[0], nx = b.st[1];
;         if (nloc == 0u) { xcd_barrier_complete(bar, b.x, nloc, nx); b.st[0] = nloc; b.st[1] = nx; }
;         const unsigned old = xb_add(&bar[XB_XSUB(b.x)], 1u);
;         const unsigned gen = old / nloc;
;         if (old + 1u == (gen + 1u) * nloc) {
;             __builtin_amdgcn_fence(__ATOMIC_RELEASE, "agent");
;             asm volatile("s_waitcnt vmcnt(0)" ::: "memory");
;             const unsigned og = xb_add(&bar[XB_TOP], 1u);
;             const unsigned tg = og / nx;
;             if (og + 1u == (tg + 1u) * nx) xb_add(&bar[XB_TOPGEN], 1u);
;             else XB_SPIN(xb_ld(&bar[XB_TOPGEN]) == tg, bar);
;             __builtin_amdgcn_fence(__ATOMIC_ACQUIRE, "agent");
;             asm volatile("s_waitcnt vmcnt(0)" ::: "memory");
;         } else {
;             XB_SPIN(xb_ld(&bar[XB_TOPGEN]) == gen, bar);
.LBB0_509:
	v_readlane_b32 s4, v253, 35
	v_readlane_b32 s5, v253, 36
	v_cvt_f32_u32_e32 v1, v2
	v_sub_u32_e32 v4, 0, v2
	v_rcp_iflag_f32_e32 v1, v1
	s_nop 1
	global_atomic_add v3, v177, v238, s[4:5] sc0
	buffer_inv sc1
	v_mul_f32_e32 v1, 0x4f7ffffe, v1
	v_cvt_u32_f32_e32 v1, v1
	v_mul_lo_u32 v4, v4, v1
	v_mul_hi_u32 v4, v1, v4
	v_add_u32_e32 v1, v1, v4
	s_waitcnt vmcnt(0)
	v_mul_hi_u32 v1, v3, v1
	v_mul_lo_u32 v4, v1, v2
	v_sub_u32_e32 v4, v3, v4
	v_add_u32_e32 v5, 1, v1
	v_cmp_ge_u32_e32 vcc, v4, v2
	v_add_u32_e32 v3, 1, v3
	s_nop 0
	v_cndmask_b32_e32 v1, v1, v5, vcc
	v_sub_u32_e32 v5, v4, v2
	v_cndmask_b32_e32 v4, v4, v5, vcc
	v_add_u32_e32 v5, 1, v1
	v_cmp_ge_u32_e32 vcc, v4, v2
	s_nop 1
	v_cndmask_b32_e32 v1, v1, v5, vcc
	v_mul_lo_u32 v4, v2, v1
	v_add_u32_e32 v2, v4, v2
	v_cmp_ne_u32_e32 vcc, v3, v2
	s_and_saveexec_b64 s[4:5], vcc
	s_xor_b64 s[4:5], exec, s[4:5]
	s_cbranch_execz .LBB0_523
	v_readlane_b32 s6, v253, 37
	v_readlane_b32 s7, v253, 38
	s_waitcnt lgkmcnt(0)
	s_nop 3
	global_load_dword v0, v177, s[6:7] sc1
	s_waitcnt vmcnt(0)
	v_cmp_eq_u32_e32 vcc, v0, v1
	s_and_saveexec_b64 s[6:7], vcc
	s_cbranch_execz .LBB0_522
	s_mov_b32 s3, 1
	s_mov_b64 s[8:9], 0
	s_branch .LBB0_513
